# attention: younger-half priority raise scoped to the MFMA tile loop only (raised at the loop header, dropped behind the loop) instead of the whole phase
# baseline (speedup 1.0000x reference)
; __device__ __forceinline__ void sc_init(f32x16& p0, f32x16& p1, float dq, float nsl2, float m_ref, int side) {
;   if (side != 0) { const float sg = (float)side; const float base0 = fmaf(sg * nsl2, dq, -m_ref), base1 = base0 - sg * 32.f * nsl2;
; #pragma unroll
;     for (int r = 0; r < 16; ++r) { const float c = -sg * nsl2 * (float)((r & 3) + 8 * (r >> 2)); p0[r] = base0 + c; p1[r] = base1 + c; }
;   } else {
; #pragma unroll
;     for (int r = 0; r < 16; ++r) { const float kv = (float)((r & 3) + 8 * (r >> 2)); const float d0 = dq - kv, d1 = d0 - 32.f;
;       p0[r] = fmaf(nsl2, __builtin_fabsf(d0), -m_ref); p1[r] = fmaf(nsl2, __builtin_fabsf(d1), -m_ref); }
;   }
; }
; __global__ void __launch_bounds__(NWAVES * 64, 2) hymba_fwd(Args args) {
;     ...
;         const float lam = ((const float*)ctl)[CW_LAM];
;         constexpr int NU = 512 + 1024;
;         for (;;) {
;             if (tid == 0) MISC[0] = atomicAdd(ctl + CW_QCTR, 1u);
;             __syncthreads();
;             const int u = (int)MISC[0];
.LBB0_290:
	v_mov_b32_e32 v177, 0
	s_barrier
	v_readfirstlane_b32 s101, v210
	s_lshr_b32 s101, s101, 8
	global_load_dword v183, v177, s[70:71] offset:256
	v_mbcnt_hi_u32_b32 v211, -1, v124
	s_add_i32 s15, 0, 0x20000
	s_mov_b32 s48, 2.0
	s_mov_b32 s50, 0x41000000
	s_mov_b32 s58, 0x41200000
	s_mov_b32 s64, 0x41800000
	s_mov_b32 s80, 0x41900000
	s_mov_b32 s82, 0x41c00000
	s_mov_b32 s86, -2.0
	s_mov_b32 s88, 0xc1000000
	s_mov_b32 s90, 0xc1200000
	s_mov_b32 s92, 0xc1800000
	s_mov_b32 s94, 0xc1900000
	s_mov_b32 s96, 0xc1c00000
	s_mov_b32 s4, 0xc1d00000
	s_waitcnt vmcnt(3)
	v_and_b32_e32 v0, 64, v211
	s_mov_b32 s11, 0
	v_mov_b32_e32 v219, s15
	s_mov_b32 s26, 0xf800000
	v_mov_b32_e32 v220, 0x260
	s_movk_i32 s27, 0xd00
	s_movk_i32 s28, 0x100
	s_add_i32 s29, 0, 0x10010
	s_mov_b32 s14, 0x41d00000
	s_mov_b32 s49, 0x40400000
	s_mov_b32 s51, 0x41100000
	s_mov_b32 s59, 0x41300000
	s_mov_b32 s65, 0x41880000
	s_mov_b32 s81, 0x41980000
	s_mov_b32 s83, 0x41c80000
	s_mov_b32 s84, 0xc2000000
	s_mov_b32 s87, 0xc0400000
	s_mov_b32 s89, 0xc1100000
	s_mov_b32 s91, 0xc1300000
	s_mov_b32 s93, 0xc1880000
	s_mov_b32 s95, 0xc1980000
	s_mov_b32 s97, 0xc1c80000
	s_mov_b32 s5, 0xc1d80000
	v_mov_b32_e32 v221, 0x358637bd
	s_movk_i32 s30, 0x7fff
	v_mov_b32_e32 v223, 0x3c800000
	v_xor_b32_e32 v214, 32, v211
	v_add_u32_e32 v213, 64, v0
	v_xor_b32_e32 v252, 1, v211
	v_xor_b32_e32 v253, 2, v211
	v_xor_b32_e32 v254, 4, v211
	v_xor_b32_e32 v212, 8, v211
	v_xor_b32_e32 v218, 16, v211
	v_mov_b32_e32 v178, 0x41d00000
	s_and_saveexec_b64 s[98:99], s[22:23]
	s_cbranch_execz .Lattn_q0
	v_mov_b32_e32 v175, 1
	global_atomic_add v175, v177, v175, s[70:71] sc0

; #define SBAR() __builtin_amdgcn_sched_barrier(0)
; #define SLOADB(k0) do { vsB0 = *(const bf16x8*)(&Vh[(size_t)((k0) + sr) * LDP + sc]); vsB1 = *(const bf16x8*)(&Vh[(size_t)((k0) + 32 + sr) * LDP + sc]); \
;     ksB0 = *(const bf16x8*)(&Kh[(size_t)((k0) + sr) * LDP + sc]); ksB1 = *(const bf16x8*)(&Kh[(size_t)((k0) + 32 + sr) * LDP + sc]); } while (0)
; __device__ __forceinline__ void attn_unit(const bf16* __restrict__ P, bf16* __restrict__ MIXIN, const float* __restrict__ gn, int seq0, int h, int q0, int nt, float kmax0, float kmax1, float slope, float lam, char* lds) {
;     ...
;   for (int j = t0 + 1; j + 1 < t1; j += 2) {
;     if (j + 2 < t1) SLOADB((j + 2) * 64); SBAR();
.LBB0_323:
	s_cmp_lg_u32 s101, 0
	s_cbranch_scc0 .Lattn_pl0
	s_setprio 1

; #define SBAR() __builtin_amdgcn_sched_barrier(0)
; __device__ __forceinline__ void sc_init(f32x16& p0, f32x16& p1, float dq, float nsl2, float m_ref, int side) {
;   if (side != 0) { const float sg = (float)side; const float base0 = fmaf(sg * nsl2, dq, -m_ref), base1 = base0 - sg * 32.f * nsl2;
; #pragma unroll
;     for (int r = 0; r < 16; ++r) { const float c = -sg * nsl2 * (float)((r & 3) + 8 * (r >> 2)); p0[r] = base0 + c; p1[r] = base1 + c; }
;   } else {
; #pragma unroll
;     for (int r = 0; r < 16; ++r) { const float kv = (float)((r & 3) + 8 * (r >> 2)); const float d0 = dq - kv, d1 = d0 - 32.f;
;       p0[r] = fmaf(nsl2, __builtin_fabsf(d0), -m_ref); p1[r] = fmaf(nsl2, __builtin_fabsf(d1), -m_ref); }
;   }
; }
; __device__ __forceinline__ void attn_unit(const bf16* __restrict__ P, bf16* __restrict__ MIXIN, const float* __restrict__ gn, int seq0, int h, int q0, int nt, float kmax0, float kmax1, float slope, float lam, char* lds) {
;     ...
;   }
;   sc_init(pB0, pB1, DQ(t1 - 1), nsl2, m_reg, SIDE(t1 - 1)); SBAR();
.Lattn_q1:
	s_or_b64 exec, exec, s[98:99]
	s_setprio 0
	s_lshl_b32 s24, s85, 7
	s_add_i32 s0, s3, -1
	v_cvt_f32_i32_e32 v96, s0
	s_cmp_gt_i32 s0, s73
	s_cselect_b64 s[0:1], -1, 0
	s_cmp_gt_i32 s3, s72
	v_fmac_f32_e32 v184, 0xc2800000, v96
	v_cndmask_b32_e64 v96, 0, -1, s[0:1]
	s_cselect_b64 vcc, -1, 0
	v_cndmask_b32_e32 v96, 1, v96, vcc
	v_cmp_ne_u32_e32 vcc, 0, v96
	s_cbranch_vccz .LBB0_347
	v_cvt_f32_i32_e32 v96, v96
	v_mul_f32_e32 v98, v180, v96
	v_mul_f32_e32 v97, 0x42000000, v96
	v_xor_b32_e32 v96, 0x80000000, v96
	v_fma_f32 v179, v98, v184, -v182
	v_pk_mul_f32 v[144:145], v[180:181], v[96:97] op_sel_hi:[0,1]
	v_mul_f32_e32 v112, 0, v144
	v_pk_mul_f32 v[114:115], v[144:145], s[14:15]
	v_pk_fma_f32 v[146:147], v[180:181], v[96:97], v[178:179] op_sel_hi:[0,1,1] neg_lo:[1,0,0] neg_hi:[1,0,0]
	v_mov_b32_e32 v113, v144
	v_pk_add_f32 v[96:97], v[112:113], v[146:147] op_sel:[0,1]
	v_pk_fma_f32 v[98:99], v[144:145], s[48:49], v[146:147] op_sel:[0,0,1] op_sel_hi:[0,1,1]
	v_pk_fma_f32 v[100:101], v[144:145], s[50:51], v[146:147] op_sel:[0,0,1] op_sel_hi:[0,1,1]
	v_pk_fma_f32 v[102:103], v[144:145], s[58:59], v[146:147] op_sel:[0,0,1] op_sel_hi:[0,1,1]
	v_pk_fma_f32 v[104:105], v[144:145], s[64:65], v[146:147] op_sel:[0,0,1] op_sel_hi:[0,1,1]
	v_pk_fma_f32 v[106:107], v[144:145], s[80:81], v[146:147] op_sel:[0,0,1] op_sel_hi:[0,1,1]
	v_pk_fma_f32 v[108:109], v[144:145], s[82:83], v[146:147] op_sel:[0,0,1] op_sel_hi:[0,1,1]
	v_pk_fma_f32 v[110:111], v[144:145], s[14:15], v[146:147] op_sel:[0,0,1] op_sel_hi:[1,1,0]
	v_mul_f32_e32 v115, 0x41d80000, v144
	v_mov_b32_e32 v146, v179
	v_pk_add_f32 v[126:127], v[146:147], v[114:115] op_sel_hi:[0,1]
	v_pk_add_f32 v[112:113], v[146:147], v[112:113] op_sel_hi:[0,1]
	v_pk_fma_f32 v[124:125], v[144:145], s[82:83], v[146:147] op_sel_hi:[0,1,0]
	v_pk_fma_f32 v[122:123], v[144:145], s[80:81], v[146:147] op_sel_hi:[0,1,0]
	v_pk_fma_f32 v[120:121], v[144:145], s[64:65], v[146:147] op_sel_hi:[0,1,0]
	v_pk_fma_f32 v[118:119], v[144:145], s[58:59], v[146:147] op_sel_hi:[0,1,0]
	v_pk_fma_f32 v[116:117], v[144:145], s[50:51], v[146:147] op_sel_hi:[0,1,0]
	v_pk_fma_f32 v[114:115], v[144:145], s[48:49], v[146:147] op_sel_hi:[0,1,0]
	v_fmac_f32_e32 v147, 0x41d80000, v144
	v_mov_b32_e32 v111, v147
	s_cbranch_execnz .LBB0_340
